# dilated attention: band mask per score as one unsigned range test (sub, cmp, cndmask) instead of two signed compares + or + index or + cndmask
# speedup vs baseline: 1.0119x; 1.0119x over previous
.LBB0_1293:
	v_lshl_or_b32 v82, s73, 4, v32
	v_readlane_b32 s8, v252, 57
	s_nop 0
	v_max_i32_e32 v16, 0x80, v82
	v_readlane_b32 s9, v252, 58
	v_lshrrev_b32_e32 v18, 2, v98
	v_add_u32_e32 v17, 0x80, v82
	v_cndmask_b32_e64 v16, v82, v16, s[8:9]
	v_and_b32_e32 v83, 12, v18
	v_sub_u32_e32 v17, v17, v16
	v_sub_u32_e32 v16, v16, v83
	v_sub_u32_e32 v18, 0, v16
	v_sub_u32_e32 v222, 1, v16
	v_sub_u32_e32 v250, 2, v16
	v_cmp_gt_u32_e32 vcc, v18, v17
	v_cmp_gt_u32_e64 s[8:9], v222, v17
	v_cmp_gt_u32_e64 s[10:11], v250, v17
	v_cndmask_b32_e32 v12, v12, v225, vcc
	v_cndmask_b32_e64 v13, v13, v225, s[8:9]
	v_cndmask_b32_e64 v14, v14, v225, s[10:11]
	v_sub_u32_e32 v18, 3, v16
	v_sub_u32_e32 v222, 16, v16
	v_sub_u32_e32 v250, 17, v16
	v_cmp_gt_u32_e32 vcc, v18, v17
	v_cmp_gt_u32_e64 s[8:9], v222, v17
	v_cmp_gt_u32_e64 s[10:11], v250, v17
	v_cndmask_b32_e32 v15, v15, v225, vcc
	v_cndmask_b32_e64 v8, v8, v225, s[8:9]
	v_cndmask_b32_e64 v9, v9, v225, s[10:11]
	v_sub_u32_e32 v18, 18, v16
	v_sub_u32_e32 v222, 19, v16
	v_sub_u32_e32 v250, 32, v16
	v_cmp_gt_u32_e32 vcc, v18, v17
	v_cmp_gt_u32_e64 s[8:9], v222, v17
	v_cmp_gt_u32_e64 s[10:11], v250, v17
	v_cndmask_b32_e32 v10, v10, v225, vcc
	v_cndmask_b32_e64 v11, v11, v225, s[8:9]
	v_cndmask_b32_e64 v19, v42, v225, s[10:11]
	v_sub_u32_e32 v18, 33, v16
	v_sub_u32_e32 v222, 34, v16
	v_sub_u32_e32 v250, 35, v16
	v_cmp_gt_u32_e32 vcc, v18, v17
	v_cmp_gt_u32_e64 s[8:9], v222, v17
	v_cmp_gt_u32_e64 s[10:11], v250, v17
	v_cndmask_b32_e32 v20, v43, v225, vcc
	v_cndmask_b32_e64 v21, v44, v225, s[8:9]
	v_cndmask_b32_e64 v22, v45, v225, s[10:11]
	v_sub_u32_e32 v18, 48, v16
	v_sub_u32_e32 v222, 49, v16
	v_sub_u32_e32 v250, 50, v16
	v_cmp_gt_u32_e32 vcc, v18, v17
	v_cmp_gt_u32_e64 s[8:9], v222, v17
	v_cmp_gt_u32_e64 s[10:11], v250, v17
	v_cndmask_b32_e32 v0, v0, v225, vcc
	v_cndmask_b32_e64 v1, v1, v225, s[8:9]
	v_cndmask_b32_e64 v2, v2, v225, s[10:11]
	v_sub_u32_e32 v18, 51, v16
	v_sub_u32_e32 v222, 64, v16
	v_sub_u32_e32 v250, 0x41, v16
	v_cmp_gt_u32_e32 vcc, v18, v17
	v_cmp_gt_u32_e64 s[8:9], v222, v17
	v_cmp_gt_u32_e64 s[10:11], v250, v17
	v_cndmask_b32_e32 v3, v3, v225, vcc
	v_cndmask_b32_e64 v23, v46, v225, s[8:9]
	v_cndmask_b32_e64 v24, v47, v225, s[10:11]
	v_sub_u32_e32 v18, 0x42, v16
	v_sub_u32_e32 v222, 0x43, v16
	v_sub_u32_e32 v250, 0x50, v16
	v_cmp_gt_u32_e32 vcc, v18, v17
	v_cmp_gt_u32_e64 s[8:9], v222, v17
	v_cmp_gt_u32_e64 s[10:11], v250, v17
	v_cndmask_b32_e32 v25, v48, v225, vcc
	v_cndmask_b32_e64 v26, v49, v225, s[8:9]
	v_cndmask_b32_e64 v27, v38, v225, s[10:11]
	v_sub_u32_e32 v18, 0x51, v16
	v_sub_u32_e32 v222, 0x52, v16
	v_sub_u32_e32 v250, 0x53, v16
	v_cmp_gt_u32_e32 vcc, v18, v17
	v_cmp_gt_u32_e64 s[8:9], v222, v17
	v_cmp_gt_u32_e64 s[10:11], v250, v17
	v_cndmask_b32_e32 v28, v39, v225, vcc
	v_cndmask_b32_e64 v29, v40, v225, s[8:9]
	v_cndmask_b32_e64 v30, v41, v225, s[10:11]
	v_sub_u32_e32 v18, 0x60, v16
	v_sub_u32_e32 v222, 0x61, v16
	v_sub_u32_e32 v250, 0x62, v16
	v_cmp_gt_u32_e32 vcc, v18, v17
	v_cmp_gt_u32_e64 s[8:9], v222, v17
	v_cmp_gt_u32_e64 s[10:11], v250, v17
	v_cndmask_b32_e32 v31, v58, v225, vcc
	v_cndmask_b32_e64 v39, v59, v225, s[8:9]
	v_cndmask_b32_e64 v40, v60, v225, s[10:11]
	v_sub_u32_e32 v18, 0x63, v16
	v_sub_u32_e32 v222, 0x70, v16
	v_sub_u32_e32 v250, 0x71, v16
	v_cmp_gt_u32_e32 vcc, v18, v17
	v_cmp_gt_u32_e64 s[8:9], v222, v17
	v_cmp_gt_u32_e64 s[10:11], v250, v17
	v_cndmask_b32_e32 v41, v61, v225, vcc
	v_cndmask_b32_e64 v4, v4, v225, s[8:9]
	v_cndmask_b32_e64 v5, v5, v225, s[10:11]
	v_sub_u32_e32 v18, 0x72, v16
	v_sub_u32_e32 v222, 0x73, v16
	v_sub_u32_e32 v250, 0x80, v16
	v_cmp_gt_u32_e32 vcc, v18, v17
	v_cmp_gt_u32_e64 s[8:9], v222, v17
	v_cmp_gt_u32_e64 s[10:11], v250, v17
	v_cndmask_b32_e32 v6, v6, v225, vcc
	v_cndmask_b32_e64 v7, v7, v225, s[8:9]
	v_cndmask_b32_e64 v42, v62, v225, s[10:11]
	v_sub_u32_e32 v18, 0x81, v16
	v_sub_u32_e32 v222, 0x82, v16
	v_sub_u32_e32 v250, 0x83, v16
	v_cmp_gt_u32_e32 vcc, v18, v17
	v_cmp_gt_u32_e64 s[8:9], v222, v17
	v_cmp_gt_u32_e64 s[10:11], v250, v17
	v_cndmask_b32_e32 v43, v63, v225, vcc
	v_cndmask_b32_e64 v44, v64, v225, s[8:9]
	v_cndmask_b32_e64 v45, v65, v225, s[10:11]
	v_sub_u32_e32 v18, 0x90, v16
	v_sub_u32_e32 v222, 0x91, v16
	v_sub_u32_e32 v250, 0x92, v16
	v_cmp_gt_u32_e32 vcc, v18, v17
	v_cmp_gt_u32_e64 s[8:9], v222, v17
	v_cmp_gt_u32_e64 s[10:11], v250, v17
	v_cndmask_b32_e32 v46, v54, v225, vcc
	v_cndmask_b32_e64 v47, v55, v225, s[8:9]
	v_cndmask_b32_e64 v48, v56, v225, s[10:11]
	v_sub_u32_e32 v18, 0x93, v16
	v_sub_u32_e32 v222, 0xa0, v16
	v_sub_u32_e32 v250, 0xa1, v16
	v_cmp_gt_u32_e32 vcc, v18, v17
	v_cmp_gt_u32_e64 s[8:9], v222, v17
	v_cmp_gt_u32_e64 s[10:11], v250, v17
	v_cndmask_b32_e32 v49, v57, v225, vcc
	v_cndmask_b32_e64 v54, v70, v225, s[8:9]
	v_cndmask_b32_e64 v55, v71, v225, s[10:11]
	v_sub_u32_e32 v18, 0xa2, v16
	v_sub_u32_e32 v222, 0xa3, v16
	v_sub_u32_e32 v250, 0xb0, v16
	v_cmp_gt_u32_e32 vcc, v18, v17
	v_cmp_gt_u32_e64 s[8:9], v222, v17
	v_cmp_gt_u32_e64 s[10:11], v250, v17
	v_cndmask_b32_e32 v56, v72, v225, vcc
	v_cndmask_b32_e64 v57, v73, v225, s[8:9]
	v_cndmask_b32_e64 v34, v34, v225, s[10:11]
	v_sub_u32_e32 v18, 0xb1, v16
	v_sub_u32_e32 v222, 0xb2, v16
	v_sub_u32_e32 v250, 0xb3, v16
	v_cmp_gt_u32_e32 vcc, v18, v17
	v_cmp_gt_u32_e64 s[8:9], v222, v17
	v_cmp_gt_u32_e64 s[10:11], v250, v17
	v_cndmask_b32_e32 v35, v35, v225, vcc
	v_cndmask_b32_e64 v62, v36, v225, s[8:9]
	v_cndmask_b32_e64 v64, v37, v225, s[10:11]
	v_sub_u32_e32 v18, 0xc0, v16
	v_sub_u32_e32 v222, 0xc1, v16
	v_sub_u32_e32 v250, 0xc2, v16
	v_cmp_gt_u32_e32 vcc, v18, v17
	v_cmp_gt_u32_e64 s[8:9], v222, v17
	v_cmp_gt_u32_e64 s[10:11], v250, v17
	v_cndmask_b32_e32 v102, v74, v225, vcc
	v_cndmask_b32_e64 v103, v75, v225, s[8:9]
	v_cndmask_b32_e64 v104, v76, v225, s[10:11]
	v_sub_u32_e32 v18, 0xc3, v16
	v_sub_u32_e32 v222, 0xd0, v16
	v_sub_u32_e32 v250, 0xd1, v16
	v_cmp_gt_u32_e32 vcc, v18, v17
	v_cmp_gt_u32_e64 s[8:9], v222, v17
	v_cmp_gt_u32_e64 s[10:11], v250, v17
	v_cndmask_b32_e32 v105, v77, v225, vcc
	v_cndmask_b32_e64 v106, v66, v225, s[8:9]
	v_cndmask_b32_e64 v107, v67, v225, s[10:11]
	v_sub_u32_e32 v18, 0xd2, v16
	v_sub_u32_e32 v222, 0xd3, v16
	v_sub_u32_e32 v250, 0xe0, v16
	v_cmp_gt_u32_e32 vcc, v18, v17
	v_cmp_gt_u32_e64 s[8:9], v222, v17
	v_cmp_gt_u32_e64 s[10:11], v250, v17
	v_cndmask_b32_e32 v108, v68, v225, vcc
	v_cndmask_b32_e64 v109, v69, v225, s[8:9]
	v_cndmask_b32_e64 v110, v78, v225, s[10:11]
	v_sub_u32_e32 v18, 0xe1, v16
	v_sub_u32_e32 v222, 0xe2, v16
	v_sub_u32_e32 v250, 0xe3, v16
	v_cmp_gt_u32_e32 vcc, v18, v17
	v_cmp_gt_u32_e64 s[8:9], v222, v17
	v_cmp_gt_u32_e64 s[10:11], v250, v17
	v_cndmask_b32_e32 v111, v79, v225, vcc
	v_cndmask_b32_e64 v112, v80, v225, s[8:9]
	v_cndmask_b32_e64 v113, v81, v225, s[10:11]
	v_sub_u32_e32 v18, 0xf0, v16
	v_sub_u32_e32 v222, 0xf1, v16
	v_sub_u32_e32 v250, 0xf2, v16
	v_cmp_gt_u32_e32 vcc, v18, v17
	v_cmp_gt_u32_e64 s[8:9], v222, v17
	v_cmp_gt_u32_e64 s[10:11], v250, v17
	v_cndmask_b32_e32 v114, v50, v225, vcc
	v_cndmask_b32_e64 v115, v51, v225, s[8:9]
	v_cndmask_b32_e64 v116, v52, v225, s[10:11]
	v_sub_u32_e32 v18, 0xf3, v16
	v_cmp_gt_u32_e32 vcc, v18, v17
	s_nop 1
	v_cndmask_b32_e32 v16, v53, v225, vcc
	v_max_f32_e32 v17, v12, v13
	v_max_f32_e32 v18, v14, v15
	s_mov_b32 s8, 0xff61b1e6
	v_max3_f32 v17, v17, v18, s8
	v_max_f32_e32 v18, v8, v9
	v_max_f32_e32 v36, v10, v11
	v_max3_f32 v17, v18, v36, v17
	v_max_f32_e32 v18, v19, v20
	v_max_f32_e32 v36, v21, v22
	v_max3_f32 v17, v18, v36, v17
	v_max_f32_e32 v18, v0, v1
	v_max_f32_e32 v36, v2, v3
	v_max3_f32 v17, v18, v36, v17
	v_max_f32_e32 v18, v23, v24
	v_max_f32_e32 v36, v25, v26
	v_max3_f32 v17, v18, v36, v17
	v_max_f32_e32 v18, v27, v28
	v_max_f32_e32 v36, v29, v30
	v_max3_f32 v17, v18, v36, v17
	v_max_f32_e32 v18, v31, v39
	v_max_f32_e32 v36, v40, v41
	v_max3_f32 v17, v18, v36, v17
	v_max_f32_e32 v18, v4, v5
	v_max_f32_e32 v36, v6, v7
	v_max3_f32 v17, v18, v36, v17
	v_max_f32_e32 v18, v42, v43
	v_max_f32_e32 v36, v44, v45
	v_max3_f32 v17, v18, v36, v17
	v_max_f32_e32 v18, v46, v47
	v_max_f32_e32 v36, v48, v49
	v_max3_f32 v17, v18, v36, v17
	v_max_f32_e32 v18, v54, v55
	v_max_f32_e32 v36, v56, v57
	v_max3_f32 v17, v18, v36, v17
	v_max_f32_e32 v18, v34, v35
	v_max_f32_e32 v36, v62, v64
	v_max3_f32 v17, v18, v36, v17
	v_max_f32_e32 v18, v102, v103
	v_max_f32_e32 v36, v104, v105
	v_max3_f32 v17, v18, v36, v17
	v_max_f32_e32 v18, v106, v107
	v_max_f32_e32 v36, v108, v109
	v_max3_f32 v17, v18, v36, v17
	v_max_f32_e32 v18, v110, v111
	v_max_f32_e32 v36, v112, v113
	v_max3_f32 v17, v18, v36, v17
	v_max_f32_e32 v18, v114, v115
	v_max_f32_e32 v36, v116, v16
	v_max3_f32 v17, v18, v36, v17
	ds_bpermute_b32 v18, v100, v17
	s_andn2_b64 vcc, exec, s[44:45]
	s_waitcnt lgkmcnt(0)
	v_max_f32_e32 v17, v17, v18
	ds_bpermute_b32 v18, v101, v17
	s_waitcnt lgkmcnt(0)
	v_max_f32_e32 v38, v17, v18
	v_sub_f32_e32 v12, v12, v38
	v_exp_f32_e32 v12, v12
	v_sub_f32_e32 v13, v13, v38
	v_exp_f32_e32 v13, v13
	v_sub_f32_e32 v14, v14, v38
	v_exp_f32_e32 v14, v14
	v_sub_f32_e32 v15, v15, v38
	v_exp_f32_e32 v15, v15
	v_sub_f32_e32 v8, v8, v38
	v_add_f32_e32 v17, 0, v12
	v_exp_f32_e32 v8, v8
	v_sub_f32_e32 v9, v9, v38
	v_add_f32_e32 v17, v13, v17
	v_exp_f32_e32 v9, v9
	v_sub_f32_e32 v10, v10, v38
	v_add_f32_e32 v17, v14, v17
	v_exp_f32_e32 v10, v10
	v_sub_f32_e32 v11, v11, v38
	v_add_f32_e32 v17, v15, v17
	v_exp_f32_e32 v11, v11
	v_sub_f32_e32 v18, v19, v38
	v_add_f32_e32 v17, v8, v17
	v_exp_f32_e32 v36, v18
	v_sub_f32_e32 v18, v20, v38
	v_add_f32_e32 v17, v9, v17
	v_exp_f32_e32 v37, v18
	v_sub_f32_e32 v18, v21, v38
	v_add_f32_e32 v17, v10, v17
	v_exp_f32_e32 v92, v18
	v_sub_f32_e32 v18, v22, v38
	v_add_f32_e32 v17, v11, v17
	v_exp_f32_e32 v93, v18
	v_sub_f32_e32 v0, v0, v38
	v_add_f32_e32 v17, v36, v17
	v_exp_f32_e32 v95, v0
	v_sub_f32_e32 v0, v1, v38
	v_add_f32_e32 v17, v37, v17
	v_exp_f32_e32 v97, v0
	v_sub_f32_e32 v0, v2, v38
	v_add_f32_e32 v17, v92, v17
	v_exp_f32_e32 v94, v0
	v_sub_f32_e32 v0, v3, v38
	v_add_f32_e32 v17, v93, v17
	v_exp_f32_e32 v96, v0
	v_sub_f32_e32 v1, v23, v38
	v_add_f32_e32 v0, v95, v17
	v_exp_f32_e32 v84, v1
	v_sub_f32_e32 v1, v24, v38
	v_add_f32_e32 v0, v97, v0
	v_exp_f32_e32 v85, v1
	v_sub_f32_e32 v1, v25, v38
	v_add_f32_e32 v0, v94, v0
	v_exp_f32_e32 v86, v1
	v_sub_f32_e32 v1, v26, v38
	v_add_f32_e32 v0, v96, v0
	v_exp_f32_e32 v87, v1
	v_sub_f32_e32 v1, v27, v38
	v_add_f32_e32 v0, v84, v0
	v_exp_f32_e32 v89, v1
	v_sub_f32_e32 v1, v28, v38
	v_add_f32_e32 v0, v85, v0
	v_exp_f32_e32 v91, v1
	v_sub_f32_e32 v1, v29, v38
	v_add_f32_e32 v0, v86, v0
	v_exp_f32_e32 v88, v1
	v_sub_f32_e32 v1, v30, v38
	v_add_f32_e32 v0, v87, v0
	v_exp_f32_e32 v90, v1
	v_sub_f32_e32 v1, v31, v38
	v_add_f32_e32 v0, v89, v0
	v_exp_f32_e32 v74, v1
	v_sub_f32_e32 v1, v39, v38
	v_add_f32_e32 v0, v91, v0
	v_exp_f32_e32 v75, v1
	v_sub_f32_e32 v1, v40, v38
	v_add_f32_e32 v0, v88, v0
	v_exp_f32_e32 v76, v1
	v_sub_f32_e32 v1, v41, v38
	v_add_f32_e32 v0, v90, v0
	v_exp_f32_e32 v77, v1
	v_sub_f32_e32 v1, v4, v38
	v_add_f32_e32 v0, v74, v0
	v_exp_f32_e32 v79, v1
	v_sub_f32_e32 v1, v5, v38
	v_add_f32_e32 v0, v75, v0
	v_exp_f32_e32 v81, v1
	v_sub_f32_e32 v1, v6, v38
	v_add_f32_e32 v0, v76, v0
	v_exp_f32_e32 v78, v1
	v_sub_f32_e32 v1, v7, v38
	v_add_f32_e32 v0, v77, v0
	v_exp_f32_e32 v80, v1
	v_sub_f32_e32 v1, v42, v38
	v_add_f32_e32 v0, v79, v0
	v_exp_f32_e32 v66, v1
	v_sub_f32_e32 v1, v43, v38
	v_add_f32_e32 v0, v81, v0
	v_exp_f32_e32 v67, v1
	v_sub_f32_e32 v1, v44, v38
	v_add_f32_e32 v0, v78, v0
	v_exp_f32_e32 v68, v1
	v_sub_f32_e32 v1, v45, v38
	v_add_f32_e32 v0, v80, v0
	v_exp_f32_e32 v69, v1
	v_sub_f32_e32 v1, v46, v38
	v_add_f32_e32 v0, v66, v0
	v_exp_f32_e32 v71, v1
	v_sub_f32_e32 v1, v47, v38
	v_add_f32_e32 v0, v67, v0
	v_exp_f32_e32 v73, v1
	v_sub_f32_e32 v1, v48, v38
	v_add_f32_e32 v0, v68, v0
	v_exp_f32_e32 v70, v1
	v_sub_f32_e32 v1, v49, v38
	v_add_f32_e32 v0, v69, v0
	v_exp_f32_e32 v72, v1
	v_sub_f32_e32 v1, v54, v38
	v_add_f32_e32 v0, v71, v0
	v_exp_f32_e32 v58, v1
	v_sub_f32_e32 v1, v55, v38
	v_add_f32_e32 v0, v73, v0
	v_exp_f32_e32 v59, v1
	v_sub_f32_e32 v1, v56, v38
	v_add_f32_e32 v0, v70, v0
	v_exp_f32_e32 v60, v1
	v_sub_f32_e32 v1, v57, v38
	v_add_f32_e32 v0, v72, v0
	v_exp_f32_e32 v61, v1
	v_sub_f32_e32 v1, v34, v38
	v_add_f32_e32 v0, v58, v0
	v_exp_f32_e32 v63, v1
	v_sub_f32_e32 v1, v35, v38
	v_add_f32_e32 v0, v59, v0
	v_exp_f32_e32 v65, v1
	v_sub_f32_e32 v1, v62, v38
	v_add_f32_e32 v0, v60, v0
	v_exp_f32_e32 v62, v1
	v_sub_f32_e32 v1, v64, v38
	v_add_f32_e32 v0, v61, v0
	v_exp_f32_e32 v64, v1
	v_sub_f32_e32 v1, v102, v38
	v_add_f32_e32 v0, v63, v0
	v_exp_f32_e32 v50, v1
	v_sub_f32_e32 v1, v103, v38
	v_add_f32_e32 v0, v65, v0
	v_exp_f32_e32 v51, v1
	v_sub_f32_e32 v1, v104, v38
	v_add_f32_e32 v0, v62, v0
	v_exp_f32_e32 v52, v1
	v_sub_f32_e32 v1, v105, v38
	v_add_f32_e32 v0, v64, v0
	v_exp_f32_e32 v53, v1
	v_sub_f32_e32 v1, v106, v38
	v_add_f32_e32 v0, v50, v0
	v_exp_f32_e32 v55, v1
	v_sub_f32_e32 v1, v107, v38
	v_add_f32_e32 v0, v51, v0
	v_exp_f32_e32 v57, v1
	v_sub_f32_e32 v1, v108, v38
	v_add_f32_e32 v0, v52, v0
	v_exp_f32_e32 v54, v1
	v_sub_f32_e32 v1, v109, v38
	v_add_f32_e32 v0, v53, v0
	v_exp_f32_e32 v56, v1
	v_sub_f32_e32 v1, v110, v38
	v_add_f32_e32 v0, v55, v0
	v_exp_f32_e32 v42, v1
	v_sub_f32_e32 v1, v111, v38
	v_add_f32_e32 v0, v57, v0
	v_exp_f32_e32 v43, v1
	v_sub_f32_e32 v1, v112, v38
	v_add_f32_e32 v0, v54, v0
	v_exp_f32_e32 v44, v1
	v_sub_f32_e32 v1, v113, v38
	v_add_f32_e32 v0, v56, v0
	v_exp_f32_e32 v45, v1
	v_sub_f32_e32 v1, v114, v38
	v_add_f32_e32 v0, v42, v0
	v_exp_f32_e32 v47, v1
	v_sub_f32_e32 v1, v115, v38
	v_add_f32_e32 v0, v43, v0
	v_exp_f32_e32 v49, v1
	v_sub_f32_e32 v1, v116, v38
	v_add_f32_e32 v0, v44, v0
	v_exp_f32_e32 v46, v1
	v_sub_f32_e32 v1, v16, v38
	v_add_f32_e32 v0, v45, v0
	v_exp_f32_e32 v48, v1
	v_add_f32_e32 v0, v47, v0
	v_add_f32_e32 v0, v49, v0
	v_add_f32_e32 v0, v46, v0
	v_add_f32_e32 v0, v48, v0
	ds_bpermute_b32 v1, v100, v0
	v_cvt_pk_bf16_f32 v2, v8, v9
	v_cvt_pk_bf16_f32 v3, v10, v11
	s_waitcnt lgkmcnt(0)
	v_add_f32_e32 v39, v0, v1
	ds_bpermute_b32 v40, v101, v39
	v_lshrrev_b32_e32 v0, 2, v32
	v_or_b32_e32 v0, v83, v0
	v_lshlrev_b32_e32 v1, 3, v98
	v_mul_u32_u24_e32 v0, 0x120, v0
	v_and_b32_e32 v1, 24, v1
	v_add3_u32 v41, s27, v0, v1
	v_cvt_pk_bf16_f32 v0, v12, v13
	v_cvt_pk_bf16_f32 v1, v14, v15
	s_cbranch_vccnz .LBB0_1295
	ds_read_b64_tr_b16 v[4:5], v41
	ds_read_b64_tr_b16 v[8:9], v41 offset:32
	ds_read_b64_tr_b16 v[12:13], v41 offset:64
	ds_read_b64_tr_b16 v[16:17], v41 offset:96
	ds_read_b64_tr_b16 v[6:7], v41 offset:4608
	ds_read_b64_tr_b16 v[10:11], v41 offset:4640
	ds_read_b64_tr_b16 v[14:15], v41 offset:4672
	ds_read_b64_tr_b16 v[18:19], v41 offset:4704
	ds_read_b64_tr_b16 v[102:103], v41 offset:128
	ds_read_b64_tr_b16 v[106:107], v41 offset:160
	ds_read_b64_tr_b16 v[110:111], v41 offset:192
	ds_read_b64_tr_b16 v[114:115], v41 offset:224
	ds_read_b64_tr_b16 v[104:105], v41 offset:4736
	ds_read_b64_tr_b16 v[108:109], v41 offset:4768
	ds_read_b64_tr_b16 v[112:113], v41 offset:4800
	ds_read_b64_tr_b16 v[116:117], v41 offset:4832
	s_waitcnt lgkmcnt(11)
	v_mfma_f32_16x16x32_bf16 v[28:31], v[4:7], v[0:3], 0
	s_waitcnt lgkmcnt(10)
	v_mfma_f32_16x16x32_bf16 v[24:27], v[8:11], v[0:3], 0
	s_waitcnt lgkmcnt(9)
	v_mfma_f32_16x16x32_bf16 v[20:23], v[12:15], v[0:3], 0
	s_waitcnt lgkmcnt(8)
	v_mfma_f32_16x16x32_bf16 v[16:19], v[16:19], v[0:3], 0
	s_waitcnt lgkmcnt(3)
	v_mfma_f32_16x16x32_bf16 v[12:15], v[102:105], v[0:3], 0
	s_waitcnt lgkmcnt(2)
	v_mfma_f32_16x16x32_bf16 v[8:11], v[106:109], v[0:3], 0
	s_waitcnt lgkmcnt(1)
	v_mfma_f32_16x16x32_bf16 v[4:7], v[110:113], v[0:3], 0
	s_waitcnt lgkmcnt(0)
	v_mfma_f32_16x16x32_bf16 v[0:3], v[114:117], v[0:3], 0
	s_branch .LBB0_1296

.LBB0_1331:
	v_lshl_or_b32 v82, s73, 4, v32
	v_readlane_b32 s8, v252, 61
	s_nop 0
	v_max_i32_e32 v16, 0x80, v82
	v_readlane_b32 s9, v252, 62
	v_lshrrev_b32_e32 v18, 2, v98
	v_add_u32_e32 v17, 0x80, v82
	v_cndmask_b32_e64 v16, v82, v16, s[8:9]
	v_and_b32_e32 v83, 12, v18
	v_sub_u32_e32 v17, v17, v16
	v_sub_u32_e32 v16, v16, v83
	v_sub_u32_e32 v18, 0, v16
	v_sub_u32_e32 v222, 1, v16
	v_sub_u32_e32 v250, 2, v16
	v_cmp_gt_u32_e32 vcc, v18, v17
	v_cmp_gt_u32_e64 s[8:9], v222, v17
	v_cmp_gt_u32_e64 s[10:11], v250, v17
	v_cndmask_b32_e32 v12, v12, v225, vcc
	v_cndmask_b32_e64 v13, v13, v225, s[8:9]
	v_cndmask_b32_e64 v14, v14, v225, s[10:11]
	v_sub_u32_e32 v18, 3, v16
	v_sub_u32_e32 v222, 16, v16
	v_sub_u32_e32 v250, 17, v16
	v_cmp_gt_u32_e32 vcc, v18, v17
	v_cmp_gt_u32_e64 s[8:9], v222, v17
	v_cmp_gt_u32_e64 s[10:11], v250, v17
	v_cndmask_b32_e32 v15, v15, v225, vcc
	v_cndmask_b32_e64 v8, v8, v225, s[8:9]
	v_cndmask_b32_e64 v9, v9, v225, s[10:11]
	v_sub_u32_e32 v18, 18, v16
	v_sub_u32_e32 v222, 19, v16
	v_sub_u32_e32 v250, 32, v16
	v_cmp_gt_u32_e32 vcc, v18, v17
	v_cmp_gt_u32_e64 s[8:9], v222, v17
	v_cmp_gt_u32_e64 s[10:11], v250, v17
	v_cndmask_b32_e32 v10, v10, v225, vcc
	v_cndmask_b32_e64 v11, v11, v225, s[8:9]
	v_cndmask_b32_e64 v19, v42, v225, s[10:11]
	v_sub_u32_e32 v18, 33, v16
	v_sub_u32_e32 v222, 34, v16
	v_sub_u32_e32 v250, 35, v16
	v_cmp_gt_u32_e32 vcc, v18, v17
	v_cmp_gt_u32_e64 s[8:9], v222, v17
	v_cmp_gt_u32_e64 s[10:11], v250, v17
	v_cndmask_b32_e32 v20, v43, v225, vcc
	v_cndmask_b32_e64 v21, v44, v225, s[8:9]
	v_cndmask_b32_e64 v22, v45, v225, s[10:11]
	v_sub_u32_e32 v18, 48, v16
	v_sub_u32_e32 v222, 49, v16
	v_sub_u32_e32 v250, 50, v16
	v_cmp_gt_u32_e32 vcc, v18, v17
	v_cmp_gt_u32_e64 s[8:9], v222, v17
	v_cmp_gt_u32_e64 s[10:11], v250, v17
	v_cndmask_b32_e32 v0, v0, v225, vcc
	v_cndmask_b32_e64 v1, v1, v225, s[8:9]
	v_cndmask_b32_e64 v2, v2, v225, s[10:11]
	v_sub_u32_e32 v18, 51, v16
	v_sub_u32_e32 v222, 64, v16
	v_sub_u32_e32 v250, 0x41, v16
	v_cmp_gt_u32_e32 vcc, v18, v17
	v_cmp_gt_u32_e64 s[8:9], v222, v17
	v_cmp_gt_u32_e64 s[10:11], v250, v17
	v_cndmask_b32_e32 v3, v3, v225, vcc
	v_cndmask_b32_e64 v23, v46, v225, s[8:9]
	v_cndmask_b32_e64 v24, v47, v225, s[10:11]
	v_sub_u32_e32 v18, 0x42, v16
	v_sub_u32_e32 v222, 0x43, v16
	v_sub_u32_e32 v250, 0x50, v16
	v_cmp_gt_u32_e32 vcc, v18, v17
	v_cmp_gt_u32_e64 s[8:9], v222, v17
	v_cmp_gt_u32_e64 s[10:11], v250, v17
	v_cndmask_b32_e32 v25, v48, v225, vcc
	v_cndmask_b32_e64 v26, v49, v225, s[8:9]
	v_cndmask_b32_e64 v27, v38, v225, s[10:11]
	v_sub_u32_e32 v18, 0x51, v16
	v_sub_u32_e32 v222, 0x52, v16
	v_sub_u32_e32 v250, 0x53, v16
	v_cmp_gt_u32_e32 vcc, v18, v17
	v_cmp_gt_u32_e64 s[8:9], v222, v17
	v_cmp_gt_u32_e64 s[10:11], v250, v17
	v_cndmask_b32_e32 v28, v39, v225, vcc
	v_cndmask_b32_e64 v29, v40, v225, s[8:9]
	v_cndmask_b32_e64 v30, v41, v225, s[10:11]
	v_sub_u32_e32 v18, 0x60, v16
	v_sub_u32_e32 v222, 0x61, v16
	v_sub_u32_e32 v250, 0x62, v16
	v_cmp_gt_u32_e32 vcc, v18, v17
	v_cmp_gt_u32_e64 s[8:9], v222, v17
	v_cmp_gt_u32_e64 s[10:11], v250, v17
	v_cndmask_b32_e32 v31, v58, v225, vcc
	v_cndmask_b32_e64 v39, v59, v225, s[8:9]
	v_cndmask_b32_e64 v40, v60, v225, s[10:11]
	v_sub_u32_e32 v18, 0x63, v16
	v_sub_u32_e32 v222, 0x70, v16
	v_sub_u32_e32 v250, 0x71, v16
	v_cmp_gt_u32_e32 vcc, v18, v17
	v_cmp_gt_u32_e64 s[8:9], v222, v17
	v_cmp_gt_u32_e64 s[10:11], v250, v17
	v_cndmask_b32_e32 v41, v61, v225, vcc
	v_cndmask_b32_e64 v4, v4, v225, s[8:9]
	v_cndmask_b32_e64 v5, v5, v225, s[10:11]
	v_sub_u32_e32 v18, 0x72, v16
	v_sub_u32_e32 v222, 0x73, v16
	v_sub_u32_e32 v250, 0x80, v16
	v_cmp_gt_u32_e32 vcc, v18, v17
	v_cmp_gt_u32_e64 s[8:9], v222, v17
	v_cmp_gt_u32_e64 s[10:11], v250, v17
	v_cndmask_b32_e32 v6, v6, v225, vcc
	v_cndmask_b32_e64 v7, v7, v225, s[8:9]
	v_cndmask_b32_e64 v42, v62, v225, s[10:11]
	v_sub_u32_e32 v18, 0x81, v16
	v_sub_u32_e32 v222, 0x82, v16
	v_sub_u32_e32 v250, 0x83, v16
	v_cmp_gt_u32_e32 vcc, v18, v17
	v_cmp_gt_u32_e64 s[8:9], v222, v17
	v_cmp_gt_u32_e64 s[10:11], v250, v17
	v_cndmask_b32_e32 v43, v63, v225, vcc
	v_cndmask_b32_e64 v44, v64, v225, s[8:9]
	v_cndmask_b32_e64 v45, v65, v225, s[10:11]
	v_sub_u32_e32 v18, 0x90, v16
	v_sub_u32_e32 v222, 0x91, v16
	v_sub_u32_e32 v250, 0x92, v16
	v_cmp_gt_u32_e32 vcc, v18, v17
	v_cmp_gt_u32_e64 s[8:9], v222, v17
	v_cmp_gt_u32_e64 s[10:11], v250, v17
	v_cndmask_b32_e32 v46, v54, v225, vcc
	v_cndmask_b32_e64 v47, v55, v225, s[8:9]
	v_cndmask_b32_e64 v48, v56, v225, s[10:11]
	v_sub_u32_e32 v18, 0x93, v16
	v_sub_u32_e32 v222, 0xa0, v16
	v_sub_u32_e32 v250, 0xa1, v16
	v_cmp_gt_u32_e32 vcc, v18, v17
	v_cmp_gt_u32_e64 s[8:9], v222, v17
	v_cmp_gt_u32_e64 s[10:11], v250, v17
	v_cndmask_b32_e32 v49, v57, v225, vcc
	v_cndmask_b32_e64 v54, v70, v225, s[8:9]
	v_cndmask_b32_e64 v55, v71, v225, s[10:11]
	v_sub_u32_e32 v18, 0xa2, v16
	v_sub_u32_e32 v222, 0xa3, v16
	v_sub_u32_e32 v250, 0xb0, v16
	v_cmp_gt_u32_e32 vcc, v18, v17
	v_cmp_gt_u32_e64 s[8:9], v222, v17
	v_cmp_gt_u32_e64 s[10:11], v250, v17
	v_cndmask_b32_e32 v56, v72, v225, vcc
	v_cndmask_b32_e64 v57, v73, v225, s[8:9]
	v_cndmask_b32_e64 v34, v34, v225, s[10:11]
	v_sub_u32_e32 v18, 0xb1, v16
	v_sub_u32_e32 v222, 0xb2, v16
	v_sub_u32_e32 v250, 0xb3, v16
	v_cmp_gt_u32_e32 vcc, v18, v17
	v_cmp_gt_u32_e64 s[8:9], v222, v17
	v_cmp_gt_u32_e64 s[10:11], v250, v17
	v_cndmask_b32_e32 v35, v35, v225, vcc
	v_cndmask_b32_e64 v62, v36, v225, s[8:9]
	v_cndmask_b32_e64 v64, v37, v225, s[10:11]
	v_sub_u32_e32 v18, 0xc0, v16
	v_sub_u32_e32 v222, 0xc1, v16
	v_sub_u32_e32 v250, 0xc2, v16
	v_cmp_gt_u32_e32 vcc, v18, v17
	v_cmp_gt_u32_e64 s[8:9], v222, v17
	v_cmp_gt_u32_e64 s[10:11], v250, v17
	v_cndmask_b32_e32 v102, v74, v225, vcc
	v_cndmask_b32_e64 v103, v75, v225, s[8:9]
	v_cndmask_b32_e64 v104, v76, v225, s[10:11]
	v_sub_u32_e32 v18, 0xc3, v16
	v_sub_u32_e32 v222, 0xd0, v16
	v_sub_u32_e32 v250, 0xd1, v16
	v_cmp_gt_u32_e32 vcc, v18, v17
	v_cmp_gt_u32_e64 s[8:9], v222, v17
	v_cmp_gt_u32_e64 s[10:11], v250, v17
	v_cndmask_b32_e32 v105, v77, v225, vcc
	v_cndmask_b32_e64 v106, v66, v225, s[8:9]
	v_cndmask_b32_e64 v107, v67, v225, s[10:11]
	v_sub_u32_e32 v18, 0xd2, v16
	v_sub_u32_e32 v222, 0xd3, v16
	v_sub_u32_e32 v250, 0xe0, v16
	v_cmp_gt_u32_e32 vcc, v18, v17
	v_cmp_gt_u32_e64 s[8:9], v222, v17
	v_cmp_gt_u32_e64 s[10:11], v250, v17
	v_cndmask_b32_e32 v108, v68, v225, vcc
	v_cndmask_b32_e64 v109, v69, v225, s[8:9]
	v_cndmask_b32_e64 v110, v78, v225, s[10:11]
	v_sub_u32_e32 v18, 0xe1, v16
	v_sub_u32_e32 v222, 0xe2, v16
	v_sub_u32_e32 v250, 0xe3, v16
	v_cmp_gt_u32_e32 vcc, v18, v17
	v_cmp_gt_u32_e64 s[8:9], v222, v17
	v_cmp_gt_u32_e64 s[10:11], v250, v17
	v_cndmask_b32_e32 v111, v79, v225, vcc
	v_cndmask_b32_e64 v112, v80, v225, s[8:9]
	v_cndmask_b32_e64 v113, v81, v225, s[10:11]
	v_sub_u32_e32 v18, 0xf0, v16
	v_sub_u32_e32 v222, 0xf1, v16
	v_sub_u32_e32 v250, 0xf2, v16
	v_cmp_gt_u32_e32 vcc, v18, v17
	v_cmp_gt_u32_e64 s[8:9], v222, v17
	v_cmp_gt_u32_e64 s[10:11], v250, v17
	v_cndmask_b32_e32 v114, v50, v225, vcc
	v_cndmask_b32_e64 v115, v51, v225, s[8:9]
	v_cndmask_b32_e64 v116, v52, v225, s[10:11]
	v_sub_u32_e32 v18, 0xf3, v16
	v_cmp_gt_u32_e32 vcc, v18, v17
	s_nop 1
	v_cndmask_b32_e32 v16, v53, v225, vcc
	v_max_f32_e32 v17, v12, v13
	v_max_f32_e32 v18, v14, v15
	s_mov_b32 s8, 0xff61b1e6
	v_max3_f32 v17, v17, v18, s8
	v_max_f32_e32 v18, v8, v9
	v_max_f32_e32 v36, v10, v11
	v_max3_f32 v17, v18, v36, v17
	v_max_f32_e32 v18, v19, v20
	v_max_f32_e32 v36, v21, v22
	v_max3_f32 v17, v18, v36, v17
	v_max_f32_e32 v18, v0, v1
	v_max_f32_e32 v36, v2, v3
	v_max3_f32 v17, v18, v36, v17
	v_max_f32_e32 v18, v23, v24
	v_max_f32_e32 v36, v25, v26
	v_max3_f32 v17, v18, v36, v17
	v_max_f32_e32 v18, v27, v28
	v_max_f32_e32 v36, v29, v30
	v_max3_f32 v17, v18, v36, v17
	v_max_f32_e32 v18, v31, v39
	v_max_f32_e32 v36, v40, v41
	v_max3_f32 v17, v18, v36, v17
	v_max_f32_e32 v18, v4, v5
	v_max_f32_e32 v36, v6, v7
	v_max3_f32 v17, v18, v36, v17
	v_max_f32_e32 v18, v42, v43
	v_max_f32_e32 v36, v44, v45
	v_max3_f32 v17, v18, v36, v17
	v_max_f32_e32 v18, v46, v47
	v_max_f32_e32 v36, v48, v49
	v_max3_f32 v17, v18, v36, v17
	v_max_f32_e32 v18, v54, v55
	v_max_f32_e32 v36, v56, v57
	v_max3_f32 v17, v18, v36, v17
	v_max_f32_e32 v18, v34, v35
	v_max_f32_e32 v36, v62, v64
	v_max3_f32 v17, v18, v36, v17
	v_max_f32_e32 v18, v102, v103
	v_max_f32_e32 v36, v104, v105
	v_max3_f32 v17, v18, v36, v17
	v_max_f32_e32 v18, v106, v107
	v_max_f32_e32 v36, v108, v109
	v_max3_f32 v17, v18, v36, v17
	v_max_f32_e32 v18, v110, v111
	v_max_f32_e32 v36, v112, v113
	v_max3_f32 v17, v18, v36, v17
	v_max_f32_e32 v18, v114, v115
	v_max_f32_e32 v36, v116, v16
	v_max3_f32 v17, v18, v36, v17
	ds_bpermute_b32 v18, v100, v17
	s_andn2_b64 vcc, exec, s[44:45]
	s_waitcnt lgkmcnt(0)
	v_max_f32_e32 v17, v17, v18
	ds_bpermute_b32 v18, v101, v17
	s_waitcnt lgkmcnt(0)
	v_max_f32_e32 v38, v17, v18
	v_sub_f32_e32 v12, v12, v38
	v_exp_f32_e32 v12, v12
	v_sub_f32_e32 v13, v13, v38
	v_exp_f32_e32 v13, v13
	v_sub_f32_e32 v14, v14, v38
	v_exp_f32_e32 v14, v14
	v_sub_f32_e32 v15, v15, v38
	v_exp_f32_e32 v15, v15
	v_sub_f32_e32 v8, v8, v38
	v_add_f32_e32 v17, 0, v12
	v_exp_f32_e32 v8, v8
	v_sub_f32_e32 v9, v9, v38
	v_add_f32_e32 v17, v13, v17
	v_exp_f32_e32 v9, v9
	v_sub_f32_e32 v10, v10, v38
	v_add_f32_e32 v17, v14, v17
	v_exp_f32_e32 v10, v10
	v_sub_f32_e32 v11, v11, v38
	v_add_f32_e32 v17, v15, v17
	v_exp_f32_e32 v11, v11
	v_sub_f32_e32 v18, v19, v38
	v_add_f32_e32 v17, v8, v17
	v_exp_f32_e32 v36, v18
	v_sub_f32_e32 v18, v20, v38
	v_add_f32_e32 v17, v9, v17
	v_exp_f32_e32 v37, v18
	v_sub_f32_e32 v18, v21, v38
	v_add_f32_e32 v17, v10, v17
	v_exp_f32_e32 v92, v18
	v_sub_f32_e32 v18, v22, v38
	v_add_f32_e32 v17, v11, v17
	v_exp_f32_e32 v93, v18
	v_sub_f32_e32 v0, v0, v38
	v_add_f32_e32 v17, v36, v17
	v_exp_f32_e32 v95, v0
	v_sub_f32_e32 v0, v1, v38
	v_add_f32_e32 v17, v37, v17
	v_exp_f32_e32 v97, v0
	v_sub_f32_e32 v0, v2, v38
	v_add_f32_e32 v17, v92, v17
	v_exp_f32_e32 v94, v0
	v_sub_f32_e32 v0, v3, v38
	v_add_f32_e32 v17, v93, v17
	v_exp_f32_e32 v96, v0
	v_sub_f32_e32 v1, v23, v38
	v_add_f32_e32 v0, v95, v17
	v_exp_f32_e32 v84, v1
	v_sub_f32_e32 v1, v24, v38
	v_add_f32_e32 v0, v97, v0
	v_exp_f32_e32 v85, v1
	v_sub_f32_e32 v1, v25, v38
	v_add_f32_e32 v0, v94, v0
	v_exp_f32_e32 v86, v1
	v_sub_f32_e32 v1, v26, v38
	v_add_f32_e32 v0, v96, v0
	v_exp_f32_e32 v87, v1
	v_sub_f32_e32 v1, v27, v38
	v_add_f32_e32 v0, v84, v0
	v_exp_f32_e32 v89, v1
	v_sub_f32_e32 v1, v28, v38
	v_add_f32_e32 v0, v85, v0
	v_exp_f32_e32 v91, v1
	v_sub_f32_e32 v1, v29, v38
	v_add_f32_e32 v0, v86, v0
	v_exp_f32_e32 v88, v1
	v_sub_f32_e32 v1, v30, v38
	v_add_f32_e32 v0, v87, v0
	v_exp_f32_e32 v90, v1
	v_sub_f32_e32 v1, v31, v38
	v_add_f32_e32 v0, v89, v0
	v_exp_f32_e32 v74, v1
	v_sub_f32_e32 v1, v39, v38
	v_add_f32_e32 v0, v91, v0
	v_exp_f32_e32 v75, v1
	v_sub_f32_e32 v1, v40, v38
	v_add_f32_e32 v0, v88, v0
	v_exp_f32_e32 v76, v1
	v_sub_f32_e32 v1, v41, v38
	v_add_f32_e32 v0, v90, v0
	v_exp_f32_e32 v77, v1
	v_sub_f32_e32 v1, v4, v38
	v_add_f32_e32 v0, v74, v0
	v_exp_f32_e32 v79, v1
	v_sub_f32_e32 v1, v5, v38
	v_add_f32_e32 v0, v75, v0
	v_exp_f32_e32 v81, v1
	v_sub_f32_e32 v1, v6, v38
	v_add_f32_e32 v0, v76, v0
	v_exp_f32_e32 v78, v1
	v_sub_f32_e32 v1, v7, v38
	v_add_f32_e32 v0, v77, v0
	v_exp_f32_e32 v80, v1
	v_sub_f32_e32 v1, v42, v38
	v_add_f32_e32 v0, v79, v0
	v_exp_f32_e32 v66, v1
	v_sub_f32_e32 v1, v43, v38
	v_add_f32_e32 v0, v81, v0
	v_exp_f32_e32 v67, v1
	v_sub_f32_e32 v1, v44, v38
	v_add_f32_e32 v0, v78, v0
	v_exp_f32_e32 v68, v1
	v_sub_f32_e32 v1, v45, v38
	v_add_f32_e32 v0, v80, v0
	v_exp_f32_e32 v69, v1
	v_sub_f32_e32 v1, v46, v38
	v_add_f32_e32 v0, v66, v0
	v_exp_f32_e32 v71, v1
	v_sub_f32_e32 v1, v47, v38
	v_add_f32_e32 v0, v67, v0
	v_exp_f32_e32 v73, v1
	v_sub_f32_e32 v1, v48, v38
	v_add_f32_e32 v0, v68, v0
	v_exp_f32_e32 v70, v1
	v_sub_f32_e32 v1, v49, v38
	v_add_f32_e32 v0, v69, v0
	v_exp_f32_e32 v72, v1
	v_sub_f32_e32 v1, v54, v38
	v_add_f32_e32 v0, v71, v0
	v_exp_f32_e32 v58, v1
	v_sub_f32_e32 v1, v55, v38
	v_add_f32_e32 v0, v73, v0
	v_exp_f32_e32 v59, v1
	v_sub_f32_e32 v1, v56, v38
	v_add_f32_e32 v0, v70, v0
	v_exp_f32_e32 v60, v1
	v_sub_f32_e32 v1, v57, v38
	v_add_f32_e32 v0, v72, v0
	v_exp_f32_e32 v61, v1
	v_sub_f32_e32 v1, v34, v38
	v_add_f32_e32 v0, v58, v0
	v_exp_f32_e32 v63, v1
	v_sub_f32_e32 v1, v35, v38
	v_add_f32_e32 v0, v59, v0
	v_exp_f32_e32 v65, v1
	v_sub_f32_e32 v1, v62, v38
	v_add_f32_e32 v0, v60, v0
	v_exp_f32_e32 v62, v1
	v_sub_f32_e32 v1, v64, v38
	v_add_f32_e32 v0, v61, v0
	v_exp_f32_e32 v64, v1
	v_sub_f32_e32 v1, v102, v38
	v_add_f32_e32 v0, v63, v0
	v_exp_f32_e32 v50, v1
	v_sub_f32_e32 v1, v103, v38
	v_add_f32_e32 v0, v65, v0
	v_exp_f32_e32 v51, v1
	v_sub_f32_e32 v1, v104, v38
	v_add_f32_e32 v0, v62, v0
	v_exp_f32_e32 v52, v1
	v_sub_f32_e32 v1, v105, v38
	v_add_f32_e32 v0, v64, v0
	v_exp_f32_e32 v53, v1
	v_sub_f32_e32 v1, v106, v38
	v_add_f32_e32 v0, v50, v0
	v_exp_f32_e32 v55, v1
	v_sub_f32_e32 v1, v107, v38
	v_add_f32_e32 v0, v51, v0
	v_exp_f32_e32 v57, v1
	v_sub_f32_e32 v1, v108, v38
	v_add_f32_e32 v0, v52, v0
	v_exp_f32_e32 v54, v1
	v_sub_f32_e32 v1, v109, v38
	v_add_f32_e32 v0, v53, v0
	v_exp_f32_e32 v56, v1
	v_sub_f32_e32 v1, v110, v38
	v_add_f32_e32 v0, v55, v0
	v_exp_f32_e32 v42, v1
	v_sub_f32_e32 v1, v111, v38
	v_add_f32_e32 v0, v57, v0
	v_exp_f32_e32 v43, v1
	v_sub_f32_e32 v1, v112, v38
	v_add_f32_e32 v0, v54, v0
	v_exp_f32_e32 v44, v1
	v_sub_f32_e32 v1, v113, v38
	v_add_f32_e32 v0, v56, v0
	v_exp_f32_e32 v45, v1
	v_sub_f32_e32 v1, v114, v38
	v_add_f32_e32 v0, v42, v0
	v_exp_f32_e32 v47, v1
	v_sub_f32_e32 v1, v115, v38
	v_add_f32_e32 v0, v43, v0
	v_exp_f32_e32 v49, v1
	v_sub_f32_e32 v1, v116, v38
	v_add_f32_e32 v0, v44, v0
	v_exp_f32_e32 v46, v1
	v_sub_f32_e32 v1, v16, v38
	v_add_f32_e32 v0, v45, v0
	v_exp_f32_e32 v48, v1
	v_add_f32_e32 v0, v47, v0
	v_add_f32_e32 v0, v49, v0
	v_add_f32_e32 v0, v46, v0
	v_add_f32_e32 v0, v48, v0
	ds_bpermute_b32 v1, v100, v0
	v_cvt_pk_bf16_f32 v2, v8, v9
	v_cvt_pk_bf16_f32 v3, v10, v11
	s_waitcnt lgkmcnt(0)
	v_add_f32_e32 v39, v0, v1
	ds_bpermute_b32 v40, v101, v39
	v_lshrrev_b32_e32 v0, 2, v32
	v_or_b32_e32 v0, v83, v0
	v_lshlrev_b32_e32 v1, 3, v98
	v_mul_u32_u24_e32 v0, 0x120, v0
	v_and_b32_e32 v1, 24, v1
	v_add3_u32 v41, s27, v0, v1
	v_cvt_pk_bf16_f32 v0, v12, v13
	v_cvt_pk_bf16_f32 v1, v14, v15
	s_cbranch_vccnz .LBB0_1333
	ds_read_b64_tr_b16 v[4:5], v41
	ds_read_b64_tr_b16 v[8:9], v41 offset:32
	ds_read_b64_tr_b16 v[12:13], v41 offset:64
	ds_read_b64_tr_b16 v[16:17], v41 offset:96
	ds_read_b64_tr_b16 v[6:7], v41 offset:4608
	ds_read_b64_tr_b16 v[10:11], v41 offset:4640
	ds_read_b64_tr_b16 v[14:15], v41 offset:4672
	ds_read_b64_tr_b16 v[18:19], v41 offset:4704
	ds_read_b64_tr_b16 v[102:103], v41 offset:128
	ds_read_b64_tr_b16 v[106:107], v41 offset:160
	ds_read_b64_tr_b16 v[110:111], v41 offset:192
	ds_read_b64_tr_b16 v[114:115], v41 offset:224
	ds_read_b64_tr_b16 v[104:105], v41 offset:4736
	ds_read_b64_tr_b16 v[108:109], v41 offset:4768
	ds_read_b64_tr_b16 v[112:113], v41 offset:4800
	ds_read_b64_tr_b16 v[116:117], v41 offset:4832
	s_waitcnt lgkmcnt(11)
	v_mfma_f32_16x16x32_bf16 v[28:31], v[4:7], v[0:3], 0
	s_waitcnt lgkmcnt(10)
	v_mfma_f32_16x16x32_bf16 v[24:27], v[8:11], v[0:3], 0
	s_waitcnt lgkmcnt(9)
	v_mfma_f32_16x16x32_bf16 v[20:23], v[12:15], v[0:3], 0
	s_waitcnt lgkmcnt(8)
	v_mfma_f32_16x16x32_bf16 v[16:19], v[16:19], v[0:3], 0
	s_waitcnt lgkmcnt(3)
	v_mfma_f32_16x16x32_bf16 v[12:15], v[102:105], v[0:3], 0
	s_waitcnt lgkmcnt(2)
	v_mfma_f32_16x16x32_bf16 v[8:11], v[106:109], v[0:3], 0
	s_waitcnt lgkmcnt(1)
	v_mfma_f32_16x16x32_bf16 v[4:7], v[110:113], v[0:3], 0
	s_waitcnt lgkmcnt(0)
	v_mfma_f32_16x16x32_bf16 v[0:3], v[114:117], v[0:3], 0
	s_branch .LBB0_1334

.LBB0_1369:
	v_readlane_b32 s8, v253, 3
	s_nop 1
	v_max_i32_e32 v16, 0x80, v82
	v_readlane_b32 s9, v253, 4
	v_lshrrev_b32_e32 v18, 2, v98
	v_add_u32_e32 v17, 0x80, v82
	v_cndmask_b32_e64 v16, v82, v16, s[8:9]
	v_and_b32_e32 v83, 12, v18
	v_sub_u32_e32 v17, v17, v16
	v_sub_u32_e32 v16, v16, v83
	v_sub_u32_e32 v18, 0, v16
	v_sub_u32_e32 v222, 1, v16
	v_sub_u32_e32 v250, 2, v16
	v_cmp_gt_u32_e32 vcc, v18, v17
	v_cmp_gt_u32_e64 s[8:9], v222, v17
	v_cmp_gt_u32_e64 s[10:11], v250, v17
	v_cndmask_b32_e32 v12, v12, v225, vcc
	v_cndmask_b32_e64 v13, v13, v225, s[8:9]
	v_cndmask_b32_e64 v14, v14, v225, s[10:11]
	v_sub_u32_e32 v18, 3, v16
	v_sub_u32_e32 v222, 16, v16
	v_sub_u32_e32 v250, 17, v16
	v_cmp_gt_u32_e32 vcc, v18, v17
	v_cmp_gt_u32_e64 s[8:9], v222, v17
	v_cmp_gt_u32_e64 s[10:11], v250, v17
	v_cndmask_b32_e32 v15, v15, v225, vcc
	v_cndmask_b32_e64 v8, v8, v225, s[8:9]
	v_cndmask_b32_e64 v9, v9, v225, s[10:11]
	v_sub_u32_e32 v18, 18, v16
	v_sub_u32_e32 v222, 19, v16
	v_sub_u32_e32 v250, 32, v16
	v_cmp_gt_u32_e32 vcc, v18, v17
	v_cmp_gt_u32_e64 s[8:9], v222, v17
	v_cmp_gt_u32_e64 s[10:11], v250, v17
	v_cndmask_b32_e32 v10, v10, v225, vcc
	v_cndmask_b32_e64 v11, v11, v225, s[8:9]
	v_cndmask_b32_e64 v19, v42, v225, s[10:11]
	v_sub_u32_e32 v18, 33, v16
	v_sub_u32_e32 v222, 34, v16
	v_sub_u32_e32 v250, 35, v16
	v_cmp_gt_u32_e32 vcc, v18, v17
	v_cmp_gt_u32_e64 s[8:9], v222, v17
	v_cmp_gt_u32_e64 s[10:11], v250, v17
	v_cndmask_b32_e32 v20, v43, v225, vcc
	v_cndmask_b32_e64 v21, v44, v225, s[8:9]
	v_cndmask_b32_e64 v22, v45, v225, s[10:11]
	v_sub_u32_e32 v18, 48, v16
	v_sub_u32_e32 v222, 49, v16
	v_sub_u32_e32 v250, 50, v16
	v_cmp_gt_u32_e32 vcc, v18, v17
	v_cmp_gt_u32_e64 s[8:9], v222, v17
	v_cmp_gt_u32_e64 s[10:11], v250, v17
	v_cndmask_b32_e32 v0, v0, v225, vcc
	v_cndmask_b32_e64 v1, v1, v225, s[8:9]
	v_cndmask_b32_e64 v2, v2, v225, s[10:11]
	v_sub_u32_e32 v18, 51, v16
	v_sub_u32_e32 v222, 64, v16
	v_sub_u32_e32 v250, 0x41, v16
	v_cmp_gt_u32_e32 vcc, v18, v17
	v_cmp_gt_u32_e64 s[8:9], v222, v17
	v_cmp_gt_u32_e64 s[10:11], v250, v17
	v_cndmask_b32_e32 v3, v3, v225, vcc
	v_cndmask_b32_e64 v23, v46, v225, s[8:9]
	v_cndmask_b32_e64 v24, v47, v225, s[10:11]
	v_sub_u32_e32 v18, 0x42, v16
	v_sub_u32_e32 v222, 0x43, v16
	v_sub_u32_e32 v250, 0x50, v16
	v_cmp_gt_u32_e32 vcc, v18, v17
	v_cmp_gt_u32_e64 s[8:9], v222, v17
	v_cmp_gt_u32_e64 s[10:11], v250, v17
	v_cndmask_b32_e32 v25, v48, v225, vcc
	v_cndmask_b32_e64 v26, v49, v225, s[8:9]
	v_cndmask_b32_e64 v27, v38, v225, s[10:11]
	v_sub_u32_e32 v18, 0x51, v16
	v_sub_u32_e32 v222, 0x52, v16
	v_sub_u32_e32 v250, 0x53, v16
	v_cmp_gt_u32_e32 vcc, v18, v17
	v_cmp_gt_u32_e64 s[8:9], v222, v17
	v_cmp_gt_u32_e64 s[10:11], v250, v17
	v_cndmask_b32_e32 v28, v39, v225, vcc
	v_cndmask_b32_e64 v29, v40, v225, s[8:9]
	v_cndmask_b32_e64 v30, v41, v225, s[10:11]
	v_sub_u32_e32 v18, 0x60, v16
	v_sub_u32_e32 v222, 0x61, v16
	v_sub_u32_e32 v250, 0x62, v16
	v_cmp_gt_u32_e32 vcc, v18, v17
	v_cmp_gt_u32_e64 s[8:9], v222, v17
	v_cmp_gt_u32_e64 s[10:11], v250, v17
	v_cndmask_b32_e32 v31, v58, v225, vcc
	v_cndmask_b32_e64 v32, v59, v225, s[8:9]
	v_cndmask_b32_e64 v39, v60, v225, s[10:11]
	v_sub_u32_e32 v18, 0x63, v16
	v_sub_u32_e32 v222, 0x70, v16
	v_sub_u32_e32 v250, 0x71, v16
	v_cmp_gt_u32_e32 vcc, v18, v17
	v_cmp_gt_u32_e64 s[8:9], v222, v17
	v_cmp_gt_u32_e64 s[10:11], v250, v17
	v_cndmask_b32_e32 v40, v61, v225, vcc
	v_cndmask_b32_e64 v4, v4, v225, s[8:9]
	v_cndmask_b32_e64 v5, v5, v225, s[10:11]
	v_sub_u32_e32 v18, 0x72, v16
	v_sub_u32_e32 v222, 0x73, v16
	v_sub_u32_e32 v250, 0x80, v16
	v_cmp_gt_u32_e32 vcc, v18, v17
	v_cmp_gt_u32_e64 s[8:9], v222, v17
	v_cmp_gt_u32_e64 s[10:11], v250, v17
	v_cndmask_b32_e32 v6, v6, v225, vcc
	v_cndmask_b32_e64 v7, v7, v225, s[8:9]
	v_cndmask_b32_e64 v41, v62, v225, s[10:11]
	v_sub_u32_e32 v18, 0x81, v16
	v_sub_u32_e32 v222, 0x82, v16
	v_sub_u32_e32 v250, 0x83, v16
	v_cmp_gt_u32_e32 vcc, v18, v17
	v_cmp_gt_u32_e64 s[8:9], v222, v17
	v_cmp_gt_u32_e64 s[10:11], v250, v17
	v_cndmask_b32_e32 v42, v63, v225, vcc
	v_cndmask_b32_e64 v43, v64, v225, s[8:9]
	v_cndmask_b32_e64 v44, v65, v225, s[10:11]
	v_sub_u32_e32 v18, 0x90, v16
	v_sub_u32_e32 v222, 0x91, v16
	v_sub_u32_e32 v250, 0x92, v16
	v_cmp_gt_u32_e32 vcc, v18, v17
	v_cmp_gt_u32_e64 s[8:9], v222, v17
	v_cmp_gt_u32_e64 s[10:11], v250, v17
	v_cndmask_b32_e32 v45, v54, v225, vcc
	v_cndmask_b32_e64 v46, v55, v225, s[8:9]
	v_cndmask_b32_e64 v47, v56, v225, s[10:11]
	v_sub_u32_e32 v18, 0x93, v16
	v_sub_u32_e32 v222, 0xa0, v16
	v_sub_u32_e32 v250, 0xa1, v16
	v_cmp_gt_u32_e32 vcc, v18, v17
	v_cmp_gt_u32_e64 s[8:9], v222, v17
	v_cmp_gt_u32_e64 s[10:11], v250, v17
	v_cndmask_b32_e32 v48, v57, v225, vcc
	v_cndmask_b32_e64 v49, v70, v225, s[8:9]
	v_cndmask_b32_e64 v54, v71, v225, s[10:11]
	v_sub_u32_e32 v18, 0xa2, v16
	v_sub_u32_e32 v222, 0xa3, v16
	v_sub_u32_e32 v250, 0xb0, v16
	v_cmp_gt_u32_e32 vcc, v18, v17
	v_cmp_gt_u32_e64 s[8:9], v222, v17
	v_cmp_gt_u32_e64 s[10:11], v250, v17
	v_cndmask_b32_e32 v55, v72, v225, vcc
	v_cndmask_b32_e64 v56, v73, v225, s[8:9]
	v_cndmask_b32_e64 v34, v34, v225, s[10:11]
	v_sub_u32_e32 v18, 0xb1, v16
	v_sub_u32_e32 v222, 0xb2, v16
	v_sub_u32_e32 v250, 0xb3, v16
	v_cmp_gt_u32_e32 vcc, v18, v17
	v_cmp_gt_u32_e64 s[8:9], v222, v17
	v_cmp_gt_u32_e64 s[10:11], v250, v17
	v_cndmask_b32_e32 v35, v35, v225, vcc
	v_cndmask_b32_e64 v57, v36, v225, s[8:9]
	v_cndmask_b32_e64 v64, v37, v225, s[10:11]
	v_sub_u32_e32 v18, 0xc0, v16
	v_sub_u32_e32 v222, 0xc1, v16
	v_sub_u32_e32 v250, 0xc2, v16
	v_cmp_gt_u32_e32 vcc, v18, v17
	v_cmp_gt_u32_e64 s[8:9], v222, v17
	v_cmp_gt_u32_e64 s[10:11], v250, v17
	v_cndmask_b32_e32 v103, v74, v225, vcc
	v_cndmask_b32_e64 v104, v75, v225, s[8:9]
	v_cndmask_b32_e64 v105, v76, v225, s[10:11]
	v_sub_u32_e32 v18, 0xc3, v16
	v_sub_u32_e32 v222, 0xd0, v16
	v_sub_u32_e32 v250, 0xd1, v16
	v_cmp_gt_u32_e32 vcc, v18, v17
	v_cmp_gt_u32_e64 s[8:9], v222, v17
	v_cmp_gt_u32_e64 s[10:11], v250, v17
	v_cndmask_b32_e32 v106, v77, v225, vcc
	v_cndmask_b32_e64 v107, v66, v225, s[8:9]
	v_cndmask_b32_e64 v108, v67, v225, s[10:11]
	v_sub_u32_e32 v18, 0xd2, v16
	v_sub_u32_e32 v222, 0xd3, v16
	v_sub_u32_e32 v250, 0xe0, v16
	v_cmp_gt_u32_e32 vcc, v18, v17
	v_cmp_gt_u32_e64 s[8:9], v222, v17
	v_cmp_gt_u32_e64 s[10:11], v250, v17
	v_cndmask_b32_e32 v109, v68, v225, vcc
	v_cndmask_b32_e64 v110, v69, v225, s[8:9]
	v_cndmask_b32_e64 v111, v78, v225, s[10:11]
	v_sub_u32_e32 v18, 0xe1, v16
	v_sub_u32_e32 v222, 0xe2, v16
	v_sub_u32_e32 v250, 0xe3, v16
	v_cmp_gt_u32_e32 vcc, v18, v17
	v_cmp_gt_u32_e64 s[8:9], v222, v17
	v_cmp_gt_u32_e64 s[10:11], v250, v17
	v_cndmask_b32_e32 v112, v79, v225, vcc
	v_cndmask_b32_e64 v113, v80, v225, s[8:9]
	v_cndmask_b32_e64 v114, v81, v225, s[10:11]
	v_sub_u32_e32 v18, 0xf0, v16
	v_sub_u32_e32 v222, 0xf1, v16
	v_sub_u32_e32 v250, 0xf2, v16
	v_cmp_gt_u32_e32 vcc, v18, v17
	v_cmp_gt_u32_e64 s[8:9], v222, v17
	v_cmp_gt_u32_e64 s[10:11], v250, v17
	v_cndmask_b32_e32 v115, v50, v225, vcc
	v_cndmask_b32_e64 v116, v51, v225, s[8:9]
	v_cndmask_b32_e64 v117, v52, v225, s[10:11]
	v_sub_u32_e32 v18, 0xf3, v16
	v_cmp_gt_u32_e32 vcc, v18, v17
	s_nop 1
	v_cndmask_b32_e32 v16, v53, v225, vcc
	v_max_f32_e32 v17, v12, v13
	v_max_f32_e32 v18, v14, v15
	s_mov_b32 s8, 0xff61b1e6
	v_max3_f32 v17, v17, v18, s8
	v_max_f32_e32 v18, v8, v9
	v_max_f32_e32 v36, v10, v11
	v_max3_f32 v17, v18, v36, v17
	v_max_f32_e32 v18, v19, v20
	v_max_f32_e32 v36, v21, v22
	v_max3_f32 v17, v18, v36, v17
	v_max_f32_e32 v18, v0, v1
	v_max_f32_e32 v36, v2, v3
	v_max3_f32 v17, v18, v36, v17
	v_max_f32_e32 v18, v23, v24
	v_max_f32_e32 v36, v25, v26
	v_max3_f32 v17, v18, v36, v17
	v_max_f32_e32 v18, v27, v28
	v_max_f32_e32 v36, v29, v30
	v_max3_f32 v17, v18, v36, v17
	v_max_f32_e32 v18, v31, v32
	v_max_f32_e32 v36, v39, v40
	v_max3_f32 v17, v18, v36, v17
	v_max_f32_e32 v18, v4, v5
	v_max_f32_e32 v36, v6, v7
	v_max3_f32 v17, v18, v36, v17
	v_max_f32_e32 v18, v41, v42
	v_max_f32_e32 v36, v43, v44
	v_max3_f32 v17, v18, v36, v17
	v_max_f32_e32 v18, v45, v46
	v_max_f32_e32 v36, v47, v48
	v_max3_f32 v17, v18, v36, v17
	v_max_f32_e32 v18, v49, v54
	v_max_f32_e32 v36, v55, v56
	v_max3_f32 v17, v18, v36, v17
	v_max_f32_e32 v18, v34, v35
	v_max_f32_e32 v36, v57, v64
	v_max3_f32 v17, v18, v36, v17
	v_max_f32_e32 v18, v103, v104
	v_max_f32_e32 v36, v105, v106
	v_max3_f32 v17, v18, v36, v17
	v_max_f32_e32 v18, v107, v108
	v_max_f32_e32 v36, v109, v110
	v_max3_f32 v17, v18, v36, v17
	v_max_f32_e32 v18, v111, v112
	v_max_f32_e32 v36, v113, v114
	v_max3_f32 v17, v18, v36, v17
	v_max_f32_e32 v18, v115, v116
	v_max_f32_e32 v36, v117, v16
	v_max3_f32 v17, v18, v36, v17
	ds_bpermute_b32 v18, v100, v17
	s_andn2_b64 vcc, exec, s[44:45]
	s_waitcnt lgkmcnt(0)
	v_max_f32_e32 v17, v17, v18
	ds_bpermute_b32 v18, v101, v17
	s_waitcnt lgkmcnt(0)
	v_max_f32_e32 v38, v17, v18
	v_sub_f32_e32 v12, v12, v38
	v_exp_f32_e32 v12, v12
	v_sub_f32_e32 v13, v13, v38
	v_exp_f32_e32 v13, v13
	v_sub_f32_e32 v14, v14, v38
	v_exp_f32_e32 v14, v14
	v_sub_f32_e32 v15, v15, v38
	v_exp_f32_e32 v15, v15
	v_sub_f32_e32 v8, v8, v38
	v_add_f32_e32 v17, 0, v12
	v_exp_f32_e32 v8, v8
	v_sub_f32_e32 v9, v9, v38
	v_add_f32_e32 v17, v13, v17
	v_exp_f32_e32 v9, v9
	v_sub_f32_e32 v10, v10, v38
	v_add_f32_e32 v17, v14, v17
	v_exp_f32_e32 v10, v10
	v_sub_f32_e32 v11, v11, v38
	v_add_f32_e32 v17, v15, v17
	v_exp_f32_e32 v11, v11
	v_sub_f32_e32 v18, v19, v38
	v_add_f32_e32 v17, v8, v17
	v_exp_f32_e32 v36, v18
	v_sub_f32_e32 v18, v20, v38
	v_add_f32_e32 v17, v9, v17
	v_exp_f32_e32 v37, v18
	v_sub_f32_e32 v18, v21, v38
	v_add_f32_e32 v17, v10, v17
	v_exp_f32_e32 v94, v18
	v_sub_f32_e32 v18, v22, v38
	v_add_f32_e32 v17, v11, v17
	v_exp_f32_e32 v95, v18
	v_sub_f32_e32 v0, v0, v38
	v_add_f32_e32 v17, v36, v17
	v_exp_f32_e32 v97, v0
	v_sub_f32_e32 v0, v1, v38
	v_add_f32_e32 v17, v37, v17
	v_exp_f32_e32 v102, v0
	v_sub_f32_e32 v0, v2, v38
	v_add_f32_e32 v17, v94, v17
	v_exp_f32_e32 v96, v0
	v_sub_f32_e32 v0, v3, v38
	v_add_f32_e32 v17, v95, v17
	v_exp_f32_e32 v99, v0
	v_sub_f32_e32 v1, v23, v38
	v_add_f32_e32 v0, v97, v17
	v_exp_f32_e32 v86, v1
	v_sub_f32_e32 v1, v24, v38
	v_add_f32_e32 v0, v102, v0
	v_exp_f32_e32 v87, v1
	v_sub_f32_e32 v1, v25, v38
	v_add_f32_e32 v0, v96, v0
	v_exp_f32_e32 v88, v1
	v_sub_f32_e32 v1, v26, v38
	v_add_f32_e32 v0, v99, v0
	v_exp_f32_e32 v89, v1
	v_sub_f32_e32 v1, v27, v38
	v_add_f32_e32 v0, v86, v0
	v_exp_f32_e32 v91, v1
	v_sub_f32_e32 v1, v28, v38
	v_add_f32_e32 v0, v87, v0
	v_exp_f32_e32 v93, v1
	v_sub_f32_e32 v1, v29, v38
	v_add_f32_e32 v0, v88, v0
	v_exp_f32_e32 v90, v1
	v_sub_f32_e32 v1, v30, v38
	v_add_f32_e32 v0, v89, v0
	v_exp_f32_e32 v92, v1
	v_sub_f32_e32 v1, v31, v38
	v_add_f32_e32 v0, v91, v0
	v_exp_f32_e32 v74, v1
	v_sub_f32_e32 v1, v32, v38
	v_add_f32_e32 v0, v93, v0
	v_exp_f32_e32 v75, v1
	v_sub_f32_e32 v1, v39, v38
	v_add_f32_e32 v0, v90, v0
	v_exp_f32_e32 v76, v1
	v_sub_f32_e32 v1, v40, v38
	v_add_f32_e32 v0, v92, v0
	v_exp_f32_e32 v77, v1
	v_sub_f32_e32 v1, v4, v38
	v_add_f32_e32 v0, v74, v0
	v_exp_f32_e32 v79, v1
	v_sub_f32_e32 v1, v5, v38
	v_add_f32_e32 v0, v75, v0
	v_exp_f32_e32 v81, v1
	v_sub_f32_e32 v1, v6, v38
	v_add_f32_e32 v0, v76, v0
	v_exp_f32_e32 v78, v1
	v_sub_f32_e32 v1, v7, v38
	v_add_f32_e32 v0, v77, v0
	v_exp_f32_e32 v80, v1
	v_sub_f32_e32 v1, v41, v38
	v_add_f32_e32 v0, v79, v0
	v_exp_f32_e32 v66, v1
	v_sub_f32_e32 v1, v42, v38
	v_add_f32_e32 v0, v81, v0
	v_exp_f32_e32 v67, v1
	v_sub_f32_e32 v1, v43, v38
	v_add_f32_e32 v0, v78, v0
	v_exp_f32_e32 v68, v1
	v_sub_f32_e32 v1, v44, v38
	v_add_f32_e32 v0, v80, v0
	v_exp_f32_e32 v69, v1
	v_sub_f32_e32 v1, v45, v38
	v_add_f32_e32 v0, v66, v0
	v_exp_f32_e32 v71, v1
	v_sub_f32_e32 v1, v46, v38
	v_add_f32_e32 v0, v67, v0
	v_exp_f32_e32 v73, v1
	v_sub_f32_e32 v1, v47, v38
	v_add_f32_e32 v0, v68, v0
	v_exp_f32_e32 v70, v1
	v_sub_f32_e32 v1, v48, v38
	v_add_f32_e32 v0, v69, v0
	v_exp_f32_e32 v72, v1
	v_sub_f32_e32 v1, v49, v38
	v_add_f32_e32 v0, v71, v0
	v_exp_f32_e32 v58, v1
	v_sub_f32_e32 v1, v54, v38
	v_add_f32_e32 v0, v73, v0
	v_exp_f32_e32 v59, v1
	v_sub_f32_e32 v1, v55, v38
	v_add_f32_e32 v0, v70, v0
	v_exp_f32_e32 v60, v1
	v_sub_f32_e32 v1, v56, v38
	v_add_f32_e32 v0, v72, v0
	v_exp_f32_e32 v61, v1
	v_sub_f32_e32 v1, v34, v38
	v_add_f32_e32 v0, v58, v0
	v_exp_f32_e32 v63, v1
	v_sub_f32_e32 v1, v35, v38
	v_add_f32_e32 v0, v59, v0
	v_exp_f32_e32 v65, v1
	v_sub_f32_e32 v1, v57, v38
	v_add_f32_e32 v0, v60, v0
	v_exp_f32_e32 v62, v1
	v_sub_f32_e32 v1, v64, v38
	v_add_f32_e32 v0, v61, v0
	v_exp_f32_e32 v64, v1
	v_sub_f32_e32 v1, v103, v38
	v_add_f32_e32 v0, v63, v0
	v_exp_f32_e32 v50, v1
	v_sub_f32_e32 v1, v104, v38
	v_add_f32_e32 v0, v65, v0
	v_exp_f32_e32 v51, v1
	v_sub_f32_e32 v1, v105, v38
	v_add_f32_e32 v0, v62, v0
	v_exp_f32_e32 v52, v1
	v_sub_f32_e32 v1, v106, v38
	v_add_f32_e32 v0, v64, v0
	v_exp_f32_e32 v53, v1
	v_sub_f32_e32 v1, v107, v38
	v_add_f32_e32 v0, v50, v0
	v_exp_f32_e32 v55, v1
	v_sub_f32_e32 v1, v108, v38
	v_add_f32_e32 v0, v51, v0
	v_exp_f32_e32 v57, v1
	v_sub_f32_e32 v1, v109, v38
	v_add_f32_e32 v0, v52, v0
	v_exp_f32_e32 v54, v1
	v_sub_f32_e32 v1, v110, v38
	v_add_f32_e32 v0, v53, v0
	v_exp_f32_e32 v56, v1
	v_sub_f32_e32 v1, v111, v38
	v_add_f32_e32 v0, v55, v0
	v_exp_f32_e32 v42, v1
	v_sub_f32_e32 v1, v112, v38
	v_add_f32_e32 v0, v57, v0
	v_exp_f32_e32 v43, v1
	v_sub_f32_e32 v1, v113, v38
	v_add_f32_e32 v0, v54, v0
	v_exp_f32_e32 v44, v1
	v_sub_f32_e32 v1, v114, v38
	v_add_f32_e32 v0, v56, v0
	v_exp_f32_e32 v45, v1
	v_sub_f32_e32 v1, v115, v38
	v_add_f32_e32 v0, v42, v0
	v_exp_f32_e32 v47, v1
	v_sub_f32_e32 v1, v116, v38
	v_add_f32_e32 v0, v43, v0
	v_exp_f32_e32 v49, v1
	v_sub_f32_e32 v1, v117, v38
	v_add_f32_e32 v0, v44, v0
	v_exp_f32_e32 v46, v1
	v_sub_f32_e32 v1, v16, v38
	v_add_f32_e32 v0, v45, v0
	v_exp_f32_e32 v48, v1
	v_add_f32_e32 v0, v47, v0
	v_add_f32_e32 v0, v49, v0
	v_add_f32_e32 v0, v46, v0
	v_add_f32_e32 v0, v48, v0
	ds_bpermute_b32 v1, v100, v0
	v_cvt_pk_bf16_f32 v2, v8, v9
	v_cvt_pk_bf16_f32 v3, v10, v11
	s_waitcnt lgkmcnt(0)
	v_add_f32_e32 v39, v0, v1
	ds_bpermute_b32 v40, v101, v39
	v_lshrrev_b32_e32 v0, 2, v85
	v_or_b32_e32 v0, v83, v0
	v_lshlrev_b32_e32 v1, 3, v98
	v_mul_u32_u24_e32 v0, 0x120, v0
	v_and_b32_e32 v1, 24, v1
	v_add3_u32 v41, s27, v0, v1
	v_cvt_pk_bf16_f32 v0, v12, v13
	v_cvt_pk_bf16_f32 v1, v14, v15
	s_cbranch_vccnz .LBB0_1371
	ds_read_b64_tr_b16 v[4:5], v41
	ds_read_b64_tr_b16 v[8:9], v41 offset:32
	ds_read_b64_tr_b16 v[12:13], v41 offset:64
	ds_read_b64_tr_b16 v[16:17], v41 offset:96
	ds_read_b64_tr_b16 v[6:7], v41 offset:4608
	ds_read_b64_tr_b16 v[10:11], v41 offset:4640
	ds_read_b64_tr_b16 v[14:15], v41 offset:4672
	ds_read_b64_tr_b16 v[18:19], v41 offset:4704
	ds_read_b64_tr_b16 v[104:105], v41 offset:128
	ds_read_b64_tr_b16 v[108:109], v41 offset:160
	ds_read_b64_tr_b16 v[112:113], v41 offset:192
	ds_read_b64_tr_b16 v[116:117], v41 offset:224
	ds_read_b64_tr_b16 v[106:107], v41 offset:4736
	ds_read_b64_tr_b16 v[110:111], v41 offset:4768
	ds_read_b64_tr_b16 v[114:115], v41 offset:4800
	ds_read_b64_tr_b16 v[118:119], v41 offset:4832
	s_waitcnt lgkmcnt(11)
	v_mfma_f32_16x16x32_bf16 v[28:31], v[4:7], v[0:3], 0
	s_waitcnt lgkmcnt(10)
	v_mfma_f32_16x16x32_bf16 v[24:27], v[8:11], v[0:3], 0
	s_waitcnt lgkmcnt(9)
	v_mfma_f32_16x16x32_bf16 v[20:23], v[12:15], v[0:3], 0
	s_waitcnt lgkmcnt(8)
	v_mfma_f32_16x16x32_bf16 v[16:19], v[16:19], v[0:3], 0
	s_waitcnt lgkmcnt(3)
	v_mfma_f32_16x16x32_bf16 v[12:15], v[104:107], v[0:3], 0
	s_waitcnt lgkmcnt(2)
	v_mfma_f32_16x16x32_bf16 v[8:11], v[108:111], v[0:3], 0
	s_waitcnt lgkmcnt(1)
	v_mfma_f32_16x16x32_bf16 v[4:7], v[112:115], v[0:3], 0
	s_waitcnt lgkmcnt(0)
	v_mfma_f32_16x16x32_bf16 v[0:3], v[116:119], v[0:3], 0
	s_branch .LBB0_1372
